# add gates-epilogue dedup: one softplus(lambda) chain per lane + ds_bpermute gather instead of 8 identical chains (bit-identical values)
# speedup vs baseline: 1.0027x; 1.0027x over previous
.LBB0_461:
	v_lshl_or_b32 v166, s78, 7, v172
	v_ashrrev_i32_e32 v167, 31, v166
	v_readlane_b32 s4, v254, 4
	v_lshlrev_b64 v[144:145], 2, v[166:167]
	v_readlane_b32 s5, v254, 5
	v_readlane_b32 s6, v254, 6
	v_readlane_b32 s7, v254, 7
	v_readlane_b32 s8, v254, 8
	v_readlane_b32 s9, v254, 9
	v_readlane_b32 s10, v254, 10
	v_readlane_b32 s11, v254, 11
	v_readlane_b32 s12, v254, 12
	v_readlane_b32 s13, v254, 13
	v_readlane_b32 s14, v254, 14
	v_readlane_b32 s15, v254, 15
	v_readlane_b32 s16, v254, 16
	v_readlane_b32 s17, v254, 17
	v_readlane_b32 s18, v254, 18
	v_readlane_b32 s19, v254, 19
	v_lshl_add_u64 v[32:33], s[16:17], 0, v[144:145]
	v_readlane_b32 s4, v254, 21
	v_readlane_b32 s5, v254, 22
	v_readlane_b32 s6, v254, 23
	v_readlane_b32 s7, v254, 24
	v_lshl_add_u64 v[44:45], s[4:5], 0, v[144:145]
	global_load_dwordx4 v[28:31], v[32:33], off offset:16
	global_load_dwordx4 v[40:43], v[32:33], off
	v_lshl_add_u64 v[148:149], s[6:7], 0, v[144:145]
	global_load_dwordx4 v[32:35], v[44:45], off offset:16
	s_nop 0
	global_load_dwordx4 v[44:47], v[44:45], off
	s_nop 0
	global_load_dwordx4 v[144:147], v[148:149], off offset:16
	s_nop 0
	v_and_b32_e32 v244, 31, v152
	v_lshlrev_b32_e32 v244, 2, v244
	v_lshrrev_b32_e32 v245, 4, v152
	v_lshlrev_b32_e32 v245, 5, v245
	v_sub_u32_e32 v244, v244, v245
	v_ashrrev_i32_e32 v245, 31, v244
	v_lshl_add_u64 v[244:245], v[148:149], 0, v[244:245]
	global_load_dword v148, v[244:245], off
	v_lshl_add_u32 v168, s0, 8, v170
	v_readlane_b32 s8, v254, 25
	v_readlane_b32 s9, v254, 26
	s_mov_b64 s[8:9], 0x40000
	v_readlane_b32 s10, v254, 27
	v_readlane_b32 s11, v254, 28
	v_readlane_b32 s12, v254, 29
	v_readlane_b32 s13, v254, 30
	v_readlane_b32 s14, v254, 31
	v_readlane_b32 s15, v254, 32
	v_readlane_b32 s16, v254, 33
	v_readlane_b32 s17, v254, 34
	v_readlane_b32 s18, v254, 35
	v_readlane_b32 s19, v254, 36
	s_waitcnt vmcnt(0)
	v_add_f32_e32 v132, v132, v28
	v_add_f32_e32 v140, v140, v40
	v_mul_f32_e32 v140, 0xbfb8aa3b, v140
	v_mul_f32_e32 v144, 0xbfb8aa3b, v144
	v_mul_f32_e32 v148, 0xbfb8aa3b, v148
	v_exp_f32_e32 v148, v148
	v_exp_f32_e32 v144, v144
	v_exp_f32_e32 v140, v140
	v_add_f32_e32 v136, v136, v44
	v_add_f32_e32 v169, 1.0, v148
	v_add_f32_e32 v187, -1.0, v169
	v_sub_f32_e32 v188, v187, v169
	v_add_f32_e32 v188, 1.0, v188
	v_sub_f32_e32 v187, v148, v187
	v_add_f32_e32 v187, v187, v188
	v_frexp_mant_f32_e32 v188, v169
	v_cmp_gt_f32_e32 vcc, s93, v188
	v_cvt_f64_f32_e32 v[188:189], v169
	v_frexp_exp_i32_f64_e32 v188, v[188:189]
	v_subbrev_co_u32_e32 v188, vcc, 0, v188, vcc
	v_sub_u32_e32 v189, 0, v188
	v_ldexp_f32 v169, v169, v189
	v_ldexp_f32 v187, v187, v189
	v_add_f32_e32 v189, -1.0, v169
	v_add_f32_e32 v190, 1.0, v189
	v_sub_f32_e32 v190, v169, v190
	v_add_f32_e32 v190, v187, v190
	v_add_f32_e32 v191, v189, v190
	v_sub_f32_e32 v189, v191, v189
	v_sub_f32_e32 v189, v190, v189
	v_add_f32_e32 v190, 1.0, v169
	v_add_f32_e32 v192, -1.0, v190
	v_sub_f32_e32 v169, v169, v192
	v_add_f32_e32 v169, v187, v169
	v_add_f32_e32 v187, v190, v169
	v_sub_f32_e32 v190, v187, v190
	v_sub_f32_e32 v169, v169, v190
	v_rcp_f32_e32 v190, v187
	v_cvt_f32_i32_e32 v188, v188
	v_cmp_neq_f32_e32 vcc, s95, v148
	v_add_f32_e32 v140, 1.0, v140
	v_mul_f32_e32 v192, v191, v190
	v_mul_f32_e32 v193, v187, v192
	v_fma_f32 v194, v192, v187, -v193
	v_fmac_f32_e32 v194, v192, v169
	v_add_f32_e32 v195, v193, v194
	v_sub_f32_e32 v196, v191, v195
	v_sub_f32_e32 v191, v191, v196
	v_sub_f32_e32 v193, v195, v193
	v_sub_f32_e32 v191, v191, v195
	v_add_f32_e32 v189, v189, v191
	v_sub_f32_e32 v191, v193, v194
	v_add_f32_e32 v189, v191, v189
	v_add_f32_e32 v191, v196, v189
	v_mul_f32_e32 v193, v190, v191
	v_mul_f32_e32 v194, v187, v193
	v_fma_f32 v187, v193, v187, -v194
	v_fmac_f32_e32 v187, v193, v169
	v_sub_f32_e32 v169, v196, v191
	v_add_f32_e32 v169, v189, v169
	v_add_f32_e32 v189, v194, v187
	v_sub_f32_e32 v195, v191, v189
	v_sub_f32_e32 v191, v191, v195
	v_sub_f32_e32 v194, v189, v194
	v_sub_f32_e32 v189, v191, v189
	v_add_f32_e32 v169, v169, v189
	v_sub_f32_e32 v187, v194, v187
	v_add_f32_e32 v169, v187, v169
	v_add_f32_e32 v187, v192, v193
	v_add_f32_e32 v169, v195, v169
	v_sub_f32_e32 v189, v187, v192
	v_mul_f32_e32 v169, v190, v169
	v_sub_f32_e32 v189, v193, v189
	v_add_f32_e32 v169, v189, v169
	v_mul_f32_e32 v192, 0x3f317218, v188
	v_add_f32_e32 v189, v187, v169
	v_fma_f32 v193, v188, s94, -v192
	v_mul_f32_e32 v190, v189, v189
	v_fmac_f32_e32 v193, 0xb102e308, v188
	v_sub_f32_e32 v187, v189, v187
	v_fmamk_f32 v191, v190, 0x3e9b6dac, v183
	v_sub_f32_e32 v169, v169, v187
	v_add_f32_e32 v187, v192, v193
	v_fmaak_f32 v191, v190, v191, 0x3f2aaada
	v_sub_f32_e32 v188, v187, v192
	v_ldexp_f32 v192, v189, 1
	v_mul_f32_e32 v189, v189, v190
	v_mul_f32_e32 v189, v189, v191
	v_add_f32_e32 v190, v192, v189
	v_sub_f32_e32 v191, v190, v192
	v_ldexp_f32 v169, v169, 1
	v_sub_f32_e32 v189, v189, v191
	v_add_f32_e32 v169, v169, v189
	v_add_f32_e32 v189, v190, v169
	v_sub_f32_e32 v190, v189, v190
	v_sub_f32_e32 v169, v169, v190
	v_add_f32_e32 v190, v187, v189
	v_sub_f32_e32 v191, v190, v187
	v_sub_f32_e32 v192, v190, v191
	v_sub_f32_e32 v188, v193, v188
	v_sub_f32_e32 v187, v187, v192
	v_sub_f32_e32 v189, v189, v191
	v_add_f32_e32 v187, v189, v187
	v_add_f32_e32 v189, v188, v169
	v_sub_f32_e32 v191, v189, v188
	v_sub_f32_e32 v192, v189, v191
	v_sub_f32_e32 v188, v188, v192
	v_sub_f32_e32 v169, v169, v191
	v_add_f32_e32 v187, v189, v187
	v_add_f32_e32 v169, v169, v188
	v_add_f32_e32 v188, v190, v187
	v_sub_f32_e32 v189, v188, v190
	v_sub_f32_e32 v187, v187, v189
	v_add_f32_e32 v169, v169, v187
	v_add_f32_e32 v169, v188, v169
	v_cndmask_b32_e32 v169, v184, v169, vcc
	v_cmp_ngt_f32_e32 vcc, -1.0, v148
	v_rcp_f32_e32 v140, v140
	v_mul_f32_e32 v136, 0xbfb8aa3b, v136
	v_cndmask_b32_e32 v169, v185, v169, vcc
	v_cmp_neq_f32_e32 vcc, -1.0, v148
	v_exp_f32_e32 v136, v136
	v_add_f32_e32 v137, v137, v45
	v_cndmask_b32_e32 v169, v186, v169, vcc
	v_cmp_lt_f32_e64 vcc, |v148|, s96
	v_add_f32_e32 v136, 1.0, v136
	v_rcp_f32_e32 v136, v136
	v_cndmask_b32_e32 v148, v169, v148, vcc
	v_add_f32_e32 v169, 1.0, v144
	v_mul_f32_e32 v187, 0xc1000000, v148
	v_lshrrev_b32_e32 v244, 4, v152
	v_lshlrev_b32_e32 v244, 5, v244
	ds_bpermute_b32 v236, v244, v187
	v_add_u32_e32 v245, 4, v244
	ds_bpermute_b32 v237, v245, v187
	v_add_u32_e32 v245, 8, v244
	ds_bpermute_b32 v238, v245, v187
	v_add_u32_e32 v245, 12, v244
	ds_bpermute_b32 v239, v245, v187
	v_add_u32_e32 v245, 16, v244
	ds_bpermute_b32 v240, v245, v187
	v_add_u32_e32 v245, 20, v244
	ds_bpermute_b32 v241, v245, v187
	v_add_u32_e32 v245, 24, v244
	ds_bpermute_b32 v242, v245, v187
	v_add_u32_e32 v245, 28, v244
	ds_bpermute_b32 v243, v245, v187
	s_waitcnt lgkmcnt(0)
	v_mov_b32_e32 v187, v236
	v_mul_f32_e32 v140, v140, v187
	v_mul_f32_e32 v140, 0x3fb8aa3b, v140
	v_exp_f32_e32 v140, v140
	v_mul_f32_e32 v137, 0xbfb8aa3b, v137
	v_exp_f32_e32 v137, v137
	v_add_f32_e32 v138, v138, v46
	v_add_f32_e32 v137, 1.0, v137
	v_rcp_f32_e32 v137, v137
	v_mov_b32_e32 v188, v240
	v_mul_f32_e32 v138, 0xbfb8aa3b, v138
	v_exp_f32_e32 v138, v138
	v_mul_f32_e32 v132, 0xbfb8aa3b, v132
	v_add_f32_e32 v138, 1.0, v138
	v_rcp_f32_e32 v138, v138
	v_exp_f32_e32 v132, v132
	v_add_f32_e32 v139, v139, v47
	v_add_f32_e32 v132, 1.0, v132
	v_mul_f32_e32 v139, 0xbfb8aa3b, v139
	v_rcp_f32_e32 v132, v132
	v_mov_b32_e32 v190, v237
	v_exp_f32_e32 v139, v139
	v_mul_f32_e32 v132, v132, v188
	v_mul_f32_e32 v132, 0x3fb8aa3b, v132
	v_add_f32_e32 v139, 1.0, v139
	v_rcp_f32_e32 v139, v139
	v_add_f32_e32 v128, v128, v32
	v_exp_f32_e32 v132, v132
	v_mul_f32_e32 v128, 0xbfb8aa3b, v128
	v_exp_f32_e32 v128, v128
	v_add_f32_e32 v129, v129, v33
	v_mov_b32_e32 v189, v241
	v_add_f32_e32 v128, 1.0, v128
	v_rcp_f32_e32 v128, v128
	v_mul_f32_e32 v129, 0xbfb8aa3b, v129
	v_exp_f32_e32 v129, v129
	s_nop 0
	v_add_f32_e32 v129, 1.0, v129
	v_rcp_f32_e32 v129, v129
	v_add_f32_e32 v124, v124, v40
	v_mul_f32_e32 v124, 0xbfb8aa3b, v124
	v_exp_f32_e32 v124, v124
	v_add_f32_e32 v120, v120, v44
	v_mov_b32_e32 v191, v238
	v_add_f32_e32 v124, 1.0, v124
	v_rcp_f32_e32 v124, v124
	v_mul_f32_e32 v120, 0xbfb8aa3b, v120
	v_mul_f32_e32 v124, v124, v187
	v_mul_f32_e32 v124, 0x3fb8aa3b, v124
	v_exp_f32_e32 v124, v124
	v_exp_f32_e32 v120, v120
	v_add_f32_e32 v121, v121, v45
	v_add_f32_e32 v120, 1.0, v120
	v_rcp_f32_e32 v120, v120
	v_mov_b32_e32 v150, v242
	v_mul_f32_e32 v121, 0xbfb8aa3b, v121
	v_exp_f32_e32 v121, v121
	v_add_f32_e32 v122, v122, v46
	v_add_f32_e32 v121, 1.0, v121
	v_rcp_f32_e32 v121, v121
	v_mul_f32_e32 v122, 0xbfb8aa3b, v122
	v_exp_f32_e32 v122, v122
	v_add_f32_e32 v116, v116, v28
	v_add_f32_e32 v122, 1.0, v122
	v_rcp_f32_e32 v122, v122
	v_mov_b32_e32 v192, v239
	v_mul_f32_e32 v144, 0xbfb8aa3b, v147
	v_exp_f32_e32 v146, v144
	v_mul_f32_e32 v116, 0xbfb8aa3b, v116
	v_exp_f32_e32 v116, v116
	v_add_f32_e32 v123, v123, v47
	v_add_f32_e32 v116, 1.0, v116
	v_ashrrev_i32_e32 v169, 31, v168
	v_mul_f32_e32 v123, 0xbfb8aa3b, v123
	v_rcp_f32_e32 v116, v116
	v_exp_f32_e32 v123, v123
	v_cmp_lt_f32_e64 vcc, |v146|, s96
	v_mul_f32_e32 v116, v116, v188
	v_add_f32_e32 v123, 1.0, v123
	v_mov_b32_e32 v151, v243
	v_lshlrev_b64 v[144:145], 10, v[168:169]
	v_lshl_add_u64 v[144:145], v[144:145], 0, v[166:167]
	v_lshlrev_b64 v[148:149], 1, v[144:145]
	v_lshl_add_u64 v[144:145], s[30:31], 0, v[148:149]
	global_load_dwordx4 v[144:147], v[144:145], off
	v_mul_f32_e32 v116, 0x3fb8aa3b, v116
	v_rcp_f32_e32 v123, v123
	v_add_f32_e32 v112, v112, v32
	v_exp_f32_e32 v116, v116
	v_mul_f32_e32 v112, 0xbfb8aa3b, v112
	v_exp_f32_e32 v112, v112
	v_add_f32_e32 v113, v113, v33
	v_mul_f32_e32 v113, 0xbfb8aa3b, v113
	v_exp_f32_e32 v113, v113
	v_add_f32_e32 v112, 1.0, v112
	v_rcp_f32_e32 v112, v112
	v_add_f32_e32 v108, v108, v40
	v_add_f32_e32 v113, 1.0, v113
	v_rcp_f32_e32 v113, v113
	v_mul_f32_e32 v108, 0xbfb8aa3b, v108
	v_exp_f32_e32 v108, v108
	v_add_f32_e32 v104, v104, v44
	v_mul_f32_e32 v104, 0xbfb8aa3b, v104
	v_exp_f32_e32 v104, v104
	v_add_f32_e32 v108, 1.0, v108
	v_rcp_f32_e32 v108, v108
	v_add_f32_e32 v105, v105, v45
	v_add_f32_e32 v104, 1.0, v104
	v_rcp_f32_e32 v104, v104
	v_mul_f32_e32 v108, v108, v187
	v_mul_f32_e32 v108, 0x3fb8aa3b, v108
	v_exp_f32_e32 v108, v108
	v_mul_f32_e32 v105, 0xbfb8aa3b, v105
	v_exp_f32_e32 v105, v105
	v_add_f32_e32 v106, v106, v46
	v_mul_f32_e32 v106, 0xbfb8aa3b, v106
	v_exp_f32_e32 v106, v106
	v_add_f32_e32 v105, 1.0, v105
	v_rcp_f32_e32 v105, v105
	v_add_f32_e32 v100, v100, v28
	v_add_f32_e32 v106, 1.0, v106
	v_rcp_f32_e32 v106, v106
	v_mul_f32_e32 v100, 0xbfb8aa3b, v100
	v_exp_f32_e32 v100, v100
	v_add_f32_e32 v107, v107, v47
	v_mul_f32_e32 v107, 0xbfb8aa3b, v107
	v_exp_f32_e32 v107, v107
	v_add_f32_e32 v100, 1.0, v100
	v_rcp_f32_e32 v100, v100
	v_add_f32_e32 v96, v96, v32
	v_add_f32_e32 v107, 1.0, v107
	v_rcp_f32_e32 v107, v107
	v_mul_f32_e32 v100, v100, v188
	v_mul_f32_e32 v100, 0x3fb8aa3b, v100
	v_exp_f32_e32 v100, v100
	v_mul_f32_e32 v96, 0xbfb8aa3b, v96
	v_exp_f32_e32 v96, v96
	v_add_f32_e32 v97, v97, v33
	v_mul_f32_e32 v97, 0xbfb8aa3b, v97
	v_exp_f32_e32 v97, v97
	v_add_f32_e32 v96, 1.0, v96
	v_rcp_f32_e32 v96, v96
	v_add_f32_e32 v92, v92, v40
	v_add_f32_e32 v97, 1.0, v97
	v_rcp_f32_e32 v97, v97
	v_mul_f32_e32 v92, 0xbfb8aa3b, v92
	v_exp_f32_e32 v92, v92
	v_add_f32_e32 v88, v88, v44
	v_mul_f32_e32 v88, 0xbfb8aa3b, v88
	v_exp_f32_e32 v88, v88
	v_add_f32_e32 v92, 1.0, v92
	v_rcp_f32_e32 v92, v92
	v_add_f32_e32 v89, v89, v45
	v_add_f32_e32 v88, 1.0, v88
	v_rcp_f32_e32 v88, v88
	v_mul_f32_e32 v92, v92, v187
	v_mul_f32_e32 v92, 0x3fb8aa3b, v92
	v_exp_f32_e32 v92, v92
	v_mul_f32_e32 v89, 0xbfb8aa3b, v89
	v_exp_f32_e32 v89, v89
	v_add_f32_e32 v90, v90, v46
	v_mul_f32_e32 v90, 0xbfb8aa3b, v90
	v_exp_f32_e32 v90, v90
	v_add_f32_e32 v89, 1.0, v89
	s_waitcnt vmcnt(0)
	v_lshlrev_b32_e32 v169, 16, v144
	v_and_b32_e32 v193, 0xffff0000, v144
	v_lshlrev_b32_e32 v196, 16, v147
	v_and_b32_e32 v144, 0xffff0000, v147
	v_sub_f32_e32 v147, 1.0, v140
	v_add_f32_e32 v140, 1.0, v140
	v_mul_f32_e32 v140, v147, v140
	v_max_f32_e32 v140, 0, v140
	v_sqrt_f32_e32 v140, v140
	v_lshlrev_b32_e32 v194, 16, v145
	v_and_b32_e32 v145, 0xffff0000, v145
	v_lshlrev_b32_e32 v195, 16, v146
	v_mul_f32_e32 v136, v136, v140
	v_add_f32_e32 v140, v141, v41
	v_mul_f32_e32 v140, 0xbfb8aa3b, v140
	v_exp_f32_e32 v140, v140
	v_and_b32_e32 v146, 0xffff0000, v146
	v_mul_f32_e32 v136, v136, v169
	v_rcp_f32_e32 v89, v89
	v_add_f32_e32 v140, 1.0, v140
	v_rcp_f32_e32 v140, v140
	v_add_f32_e32 v90, 1.0, v90
	v_rcp_f32_e32 v90, v90
	v_add_f32_e32 v84, v84, v28
	v_mul_f32_e32 v140, v140, v190
	v_mul_f32_e32 v140, 0x3fb8aa3b, v140
	v_exp_f32_e32 v140, v140
	v_mul_f32_e32 v84, 0xbfb8aa3b, v84
	v_exp_f32_e32 v84, v84
	v_add_f32_e32 v91, v91, v47
	v_sub_f32_e32 v141, 1.0, v140
	v_add_f32_e32 v140, 1.0, v140
	v_mul_f32_e32 v140, v141, v140
	v_max_f32_e32 v140, 0, v140
	v_sqrt_f32_e32 v140, v140
	v_add_f32_e32 v84, 1.0, v84
	v_mul_f32_e32 v91, 0xbfb8aa3b, v91
	v_rcp_f32_e32 v84, v84
	v_mul_f32_e32 v137, v137, v140
	v_add_f32_e32 v140, v142, v42
	v_mul_f32_e32 v140, 0xbfb8aa3b, v140
	v_exp_f32_e32 v140, v140
	v_mul_f32_e32 v137, v137, v193
	v_exp_f32_e32 v91, v91
	v_mul_f32_e32 v84, v84, v188
	v_add_f32_e32 v140, 1.0, v140
	v_rcp_f32_e32 v140, v140
	v_add_f32_e32 v91, 1.0, v91
	v_mul_f32_e32 v84, 0x3fb8aa3b, v84
	v_rcp_f32_e32 v91, v91
	v_mul_f32_e32 v140, v140, v191
	v_mul_f32_e32 v140, 0x3fb8aa3b, v140
	v_exp_f32_e32 v140, v140
	v_add_f32_e32 v80, v80, v32
	v_exp_f32_e32 v84, v84
	v_mul_f32_e32 v80, 0xbfb8aa3b, v80
	v_sub_f32_e32 v142, 1.0, v140
	v_add_f32_e32 v140, 1.0, v140
	v_mul_f32_e32 v140, v142, v140
	v_max_f32_e32 v140, 0, v140
	v_sqrt_f32_e32 v140, v140
	v_exp_f32_e32 v80, v80
	v_add_f32_e32 v81, v81, v33
	v_mul_f32_e32 v81, 0xbfb8aa3b, v81
	v_mul_f32_e32 v138, v138, v140
	v_add_f32_e32 v140, v143, v43
	v_mul_f32_e32 v140, 0xbfb8aa3b, v140
	v_exp_f32_e32 v140, v140
	v_mul_f32_e32 v138, v138, v194
	v_add_f32_e32 v80, 1.0, v80
	v_rcp_f32_e32 v80, v80
	v_add_f32_e32 v140, 1.0, v140
	v_rcp_f32_e32 v140, v140
	v_exp_f32_e32 v81, v81
	v_add_f32_e32 v76, v76, v40
	v_mul_f32_e32 v76, 0xbfb8aa3b, v76
	v_mul_f32_e32 v140, v140, v192
	v_mul_f32_e32 v140, 0x3fb8aa3b, v140
	v_exp_f32_e32 v140, v140
	v_add_f32_e32 v81, 1.0, v81
	v_rcp_f32_e32 v81, v81
	v_exp_f32_e32 v76, v76
	v_sub_f32_e32 v143, 1.0, v140
	v_add_f32_e32 v140, 1.0, v140
	v_mul_f32_e32 v140, v143, v140
	v_max_f32_e32 v140, 0, v140
	v_sqrt_f32_e32 v140, v140
	v_add_f32_e32 v76, 1.0, v76
	v_rcp_f32_e32 v76, v76
	v_add_f32_e32 v72, v72, v44
	v_mul_f32_e32 v139, v139, v140
	v_sub_f32_e32 v140, 1.0, v132
	v_add_f32_e32 v132, 1.0, v132
	v_mul_f32_e32 v132, v140, v132
	v_max_f32_e32 v132, 0, v132
	v_sqrt_f32_e32 v132, v132
	v_mul_f32_e32 v139, v139, v145
	v_mul_f32_e32 v76, v76, v187
	v_mul_f32_e32 v76, 0x3fb8aa3b, v76
	v_mul_f32_e32 v128, v128, v132
	v_mul_f32_e32 v145, v128, v195
	v_add_f32_e32 v128, v133, v29
	v_mul_f32_e32 v128, 0xbfb8aa3b, v128
	v_exp_f32_e32 v128, v128
	v_exp_f32_e32 v76, v76
	v_mul_f32_e32 v72, 0xbfb8aa3b, v72
	v_exp_f32_e32 v72, v72
	v_add_f32_e32 v128, 1.0, v128
	v_rcp_f32_e32 v128, v128
	v_add_f32_e32 v73, v73, v45
	v_add_f32_e32 v72, 1.0, v72
	v_rcp_f32_e32 v72, v72
	v_mul_f32_e32 v128, v128, v189
	v_mul_f32_e32 v128, 0x3fb8aa3b, v128
	v_exp_f32_e32 v128, v128
	v_mul_f32_e32 v73, 0xbfb8aa3b, v73
	v_exp_f32_e32 v73, v73
	v_add_f32_e32 v74, v74, v46
	v_sub_f32_e32 v132, 1.0, v128
	v_add_f32_e32 v128, 1.0, v128
	v_mul_f32_e32 v128, v132, v128
	v_max_f32_e32 v128, 0, v128
	v_sqrt_f32_e32 v128, v128
	v_add_f32_e32 v73, 1.0, v73
	v_rcp_f32_e32 v73, v73
	v_mul_f32_e32 v74, 0xbfb8aa3b, v74
	v_mul_f32_e32 v128, v129, v128
	v_mul_f32_e32 v146, v128, v146
	v_add_f32_e32 v128, v134, v30
	v_mul_f32_e32 v128, 0xbfb8aa3b, v128
	v_exp_f32_e32 v128, v128
	v_add_f32_e32 v129, v130, v34
	v_mul_f32_e32 v129, 0xbfb8aa3b, v129
	v_exp_f32_e32 v129, v129
	v_add_f32_e32 v128, 1.0, v128
	v_rcp_f32_e32 v128, v128
	v_exp_f32_e32 v74, v74
	v_add_f32_e32 v129, 1.0, v129
	v_rcp_f32_e32 v129, v129
	v_mul_f32_e32 v128, v128, v150
	v_mul_f32_e32 v128, 0x3fb8aa3b, v128
	v_exp_f32_e32 v128, v128
	v_add_f32_e32 v74, 1.0, v74
	v_rcp_f32_e32 v74, v74
	v_add_f32_e32 v68, v68, v28
	v_sub_f32_e32 v133, 1.0, v128
	v_add_f32_e32 v128, 1.0, v128
	v_mul_f32_e32 v128, v133, v128
	v_max_f32_e32 v128, 0, v128
	v_sqrt_f32_e32 v128, v128
	v_mul_f32_e32 v68, 0xbfb8aa3b, v68
	v_exp_f32_e32 v68, v68
	v_add_f32_e32 v75, v75, v47
	v_mul_f32_e32 v128, v129, v128
	v_mul_f32_e32 v134, v128, v196
	v_add_f32_e32 v128, v135, v31
	v_mul_f32_e32 v128, 0xbfb8aa3b, v128
	v_exp_f32_e32 v128, v128
	v_add_f32_e32 v129, v131, v35
	v_mul_f32_e32 v129, 0xbfb8aa3b, v129
	v_exp_f32_e32 v129, v129
	v_add_f32_e32 v128, 1.0, v128
	v_rcp_f32_e32 v128, v128
	v_add_f32_e32 v68, 1.0, v68
	v_add_f32_e32 v129, 1.0, v129
	v_rcp_f32_e32 v129, v129
	v_mul_f32_e32 v128, v128, v151
	v_mul_f32_e32 v128, 0x3fb8aa3b, v128
	v_exp_f32_e32 v128, v128
	v_mul_f32_e32 v75, 0xbfb8aa3b, v75
	v_rcp_f32_e32 v68, v68
	v_exp_f32_e32 v75, v75
	v_sub_f32_e32 v131, 1.0, v128
	v_add_f32_e32 v128, 1.0, v128
	v_mul_f32_e32 v128, v131, v128
	v_max_f32_e32 v128, 0, v128
	v_sqrt_f32_e32 v128, v128
	v_mul_f32_e32 v68, v68, v188
	v_add_f32_e32 v75, 1.0, v75
	v_mul_f32_e32 v68, 0x3fb8aa3b, v68
	v_mul_f32_e32 v128, v129, v128
	v_mul_f32_e32 v135, v128, v144
	v_cvt_pk_bf16_f32 v128, v147, v141
	v_cvt_pk_bf16_f32 v129, v142, v143
	v_cvt_pk_bf16_f32 v130, v140, v132
	v_cvt_pk_bf16_f32 v131, v133, v131
	v_lshl_add_u64 v[132:133], s[20:21], 0, v[148:149]
	global_store_dwordx4 v[132:133], v[128:131], off sc0 sc1
	s_nop 1
	v_cvt_pk_bf16_f32 v128, v136, v137
	v_cvt_pk_bf16_f32 v129, v138, v139
	v_cvt_pk_bf16_f32 v130, v145, v146
	v_cvt_pk_bf16_f32 v131, v134, v135
	v_lshl_add_u64 v[132:133], s[34:35], 0, v[148:149]
	global_store_dwordx4 v[132:133], v[128:131], off sc0 sc1
	s_nop 1
	v_or_b32_e32 v128, 16, v168
	v_ashrrev_i32_e32 v129, 31, v128
	v_lshlrev_b64 v[128:129], 10, v[128:129]
	v_lshl_add_u64 v[128:129], v[128:129], 0, v[166:167]
	v_lshlrev_b64 v[128:129], 1, v[128:129]
	v_lshl_add_u64 v[130:131], s[30:31], 0, v[128:129]
	global_load_dwordx4 v[130:133], v[130:131], off
	v_rcp_f32_e32 v75, v75
	v_add_f32_e32 v64, v64, v32
	v_exp_f32_e32 v68, v68
	v_mul_f32_e32 v64, 0xbfb8aa3b, v64
	v_exp_f32_e32 v64, v64
	v_add_f32_e32 v65, v65, v33
	v_mul_f32_e32 v65, 0xbfb8aa3b, v65
	v_exp_f32_e32 v65, v65
	v_add_f32_e32 v64, 1.0, v64
	v_rcp_f32_e32 v64, v64
	v_add_f32_e32 v60, v60, v40
	v_add_f32_e32 v65, 1.0, v65
	v_rcp_f32_e32 v65, v65
	v_mul_f32_e32 v60, 0xbfb8aa3b, v60
	v_exp_f32_e32 v60, v60
	v_add_f32_e32 v56, v56, v44
	v_mul_f32_e32 v56, 0xbfb8aa3b, v56
	v_exp_f32_e32 v56, v56
	v_add_f32_e32 v60, 1.0, v60
	v_rcp_f32_e32 v60, v60
	v_add_f32_e32 v57, v57, v45
	v_add_f32_e32 v56, 1.0, v56
	v_rcp_f32_e32 v56, v56
	v_mul_f32_e32 v60, v60, v187
	v_mul_f32_e32 v60, 0x3fb8aa3b, v60
	v_exp_f32_e32 v60, v60
	v_mul_f32_e32 v57, 0xbfb8aa3b, v57
	v_exp_f32_e32 v57, v57
	v_add_f32_e32 v58, v58, v46
	v_mul_f32_e32 v58, 0xbfb8aa3b, v58
	v_exp_f32_e32 v58, v58
	v_add_f32_e32 v57, 1.0, v57
	v_rcp_f32_e32 v57, v57
	v_add_f32_e32 v52, v52, v28
	v_add_f32_e32 v58, 1.0, v58
	v_rcp_f32_e32 v58, v58
	v_mul_f32_e32 v52, 0xbfb8aa3b, v52
	v_exp_f32_e32 v52, v52
	v_add_f32_e32 v59, v59, v47
	v_mul_f32_e32 v59, 0xbfb8aa3b, v59
	v_exp_f32_e32 v59, v59
	v_add_f32_e32 v52, 1.0, v52
	v_rcp_f32_e32 v52, v52
	v_add_f32_e32 v48, v48, v32
	v_add_f32_e32 v59, 1.0, v59
	v_rcp_f32_e32 v59, v59
	v_mul_f32_e32 v52, v52, v188
	v_mul_f32_e32 v52, 0x3fb8aa3b, v52
	v_exp_f32_e32 v52, v52
	v_mul_f32_e32 v48, 0xbfb8aa3b, v48
	v_exp_f32_e32 v48, v48
	v_add_f32_e32 v49, v49, v33
	v_mul_f32_e32 v49, 0xbfb8aa3b, v49
	v_exp_f32_e32 v49, v49
	v_add_f32_e32 v48, 1.0, v48
	v_rcp_f32_e32 v48, v48
	v_add_f32_e32 v36, v36, v40
	v_add_f32_e32 v49, 1.0, v49
	v_rcp_f32_e32 v49, v49
	v_mul_f32_e32 v36, 0xbfb8aa3b, v36
	v_exp_f32_e32 v36, v36
	v_add_f32_e32 v24, v24, v44
	v_mul_f32_e32 v24, 0xbfb8aa3b, v24
	v_exp_f32_e32 v24, v24
	v_add_f32_e32 v36, 1.0, v36
	v_rcp_f32_e32 v36, v36
	v_add_f32_e32 v25, v25, v45
	v_add_f32_e32 v24, 1.0, v24
	v_rcp_f32_e32 v24, v24
	v_mul_f32_e32 v36, v36, v187
	v_mul_f32_e32 v36, 0x3fb8aa3b, v36
	v_exp_f32_e32 v36, v36
	v_mul_f32_e32 v25, 0xbfb8aa3b, v25
	v_exp_f32_e32 v25, v25
	v_add_f32_e32 v26, v26, v46
	v_mul_f32_e32 v26, 0xbfb8aa3b, v26
	v_exp_f32_e32 v26, v26
	v_add_f32_e32 v25, 1.0, v25
	v_rcp_f32_e32 v25, v25
	s_waitcnt vmcnt(0)
	v_lshlrev_b32_e32 v134, 16, v130
	v_and_b32_e32 v135, 0xffff0000, v130
	v_lshlrev_b32_e32 v138, 16, v133
	v_and_b32_e32 v130, 0xffff0000, v133
	v_sub_f32_e32 v133, 1.0, v124
	v_add_f32_e32 v124, 1.0, v124
	v_mul_f32_e32 v124, v133, v124
	v_max_f32_e32 v124, 0, v124
	v_sqrt_f32_e32 v124, v124
	v_lshlrev_b32_e32 v136, 16, v131
	v_and_b32_e32 v131, 0xffff0000, v131
	v_lshlrev_b32_e32 v137, 16, v132
	v_mul_f32_e32 v120, v120, v124
	v_add_f32_e32 v124, v125, v41
	v_mul_f32_e32 v124, 0xbfb8aa3b, v124
	v_exp_f32_e32 v124, v124
	v_and_b32_e32 v132, 0xffff0000, v132
	v_mul_f32_e32 v120, v120, v134
	v_add_f32_e32 v26, 1.0, v26
	v_add_f32_e32 v124, 1.0, v124
	v_rcp_f32_e32 v124, v124
	v_rcp_f32_e32 v26, v26
	v_add_f32_e32 v20, v20, v28
	v_mul_f32_e32 v20, 0xbfb8aa3b, v20
	v_mul_f32_e32 v124, v124, v190
	v_mul_f32_e32 v124, 0x3fb8aa3b, v124
	v_exp_f32_e32 v124, v124
	v_exp_f32_e32 v20, v20
	v_add_f32_e32 v27, v27, v47
	v_mul_f32_e32 v27, 0xbfb8aa3b, v27
	v_sub_f32_e32 v125, 1.0, v124
	v_add_f32_e32 v124, 1.0, v124
	v_mul_f32_e32 v124, v125, v124
	v_max_f32_e32 v124, 0, v124
	v_sqrt_f32_e32 v124, v124
	v_add_f32_e32 v20, 1.0, v20
	v_rcp_f32_e32 v20, v20
	v_exp_f32_e32 v27, v27
	v_mul_f32_e32 v121, v121, v124
	v_add_f32_e32 v124, v126, v42
	v_mul_f32_e32 v124, 0xbfb8aa3b, v124
	v_exp_f32_e32 v124, v124
	v_mul_f32_e32 v121, v121, v135
	v_mul_f32_e32 v20, v20, v188
	v_add_f32_e32 v27, 1.0, v27
	v_add_f32_e32 v124, 1.0, v124
	v_rcp_f32_e32 v124, v124
	v_mul_f32_e32 v20, 0x3fb8aa3b, v20
	v_rcp_f32_e32 v27, v27
	v_add_f32_e32 v16, v16, v32
	v_mul_f32_e32 v124, v124, v191
	v_mul_f32_e32 v124, 0x3fb8aa3b, v124
	v_exp_f32_e32 v124, v124
	v_exp_f32_e32 v20, v20
	v_mul_f32_e32 v16, 0xbfb8aa3b, v16
	v_exp_f32_e32 v16, v16
	v_sub_f32_e32 v126, 1.0, v124
	v_add_f32_e32 v124, 1.0, v124
	v_mul_f32_e32 v124, v126, v124
	v_max_f32_e32 v124, 0, v124
	v_sqrt_f32_e32 v124, v124
	v_add_f32_e32 v16, 1.0, v16
	v_rcp_f32_e32 v16, v16
	v_add_f32_e32 v17, v17, v33
	v_mul_f32_e32 v122, v122, v124
	v_add_f32_e32 v124, v127, v43
	v_mul_f32_e32 v124, 0xbfb8aa3b, v124
	v_exp_f32_e32 v124, v124
	v_mul_f32_e32 v122, v122, v136
	v_mul_f32_e32 v17, 0xbfb8aa3b, v17
	v_exp_f32_e32 v17, v17
	v_add_f32_e32 v124, 1.0, v124
	v_rcp_f32_e32 v124, v124
	v_add_f32_e32 v12, v12, v40
	v_add_f32_e32 v17, 1.0, v17
	v_rcp_f32_e32 v17, v17
	v_mul_f32_e32 v124, v124, v192
	v_mul_f32_e32 v124, 0x3fb8aa3b, v124
	v_exp_f32_e32 v124, v124
	v_mul_f32_e32 v12, 0xbfb8aa3b, v12
	v_exp_f32_e32 v12, v12
	v_add_f32_e32 v8, v8, v44
	v_sub_f32_e32 v127, 1.0, v124
	v_add_f32_e32 v124, 1.0, v124
	v_mul_f32_e32 v124, v127, v124
	v_max_f32_e32 v124, 0, v124
	v_sqrt_f32_e32 v124, v124
	v_add_f32_e32 v12, 1.0, v12
	v_rcp_f32_e32 v12, v12
	v_mul_f32_e32 v8, 0xbfb8aa3b, v8
	v_mul_f32_e32 v123, v123, v124
	v_sub_f32_e32 v124, 1.0, v116
	v_add_f32_e32 v116, 1.0, v116
	v_mul_f32_e32 v116, v124, v116
	v_max_f32_e32 v116, 0, v116
	v_sqrt_f32_e32 v116, v116
	v_mul_f32_e32 v123, v123, v131
	v_mul_f32_e32 v12, v12, v187
	v_mul_f32_e32 v12, 0x3fb8aa3b, v12
	v_mul_f32_e32 v112, v112, v116
	v_mul_f32_e32 v131, v112, v137
	v_add_f32_e32 v112, v117, v29
	v_mul_f32_e32 v112, 0xbfb8aa3b, v112
	v_exp_f32_e32 v112, v112
	v_exp_f32_e32 v12, v12
	v_exp_f32_e32 v8, v8
	v_add_f32_e32 v9, v9, v45
	v_add_f32_e32 v112, 1.0, v112
	v_rcp_f32_e32 v112, v112
	v_add_f32_e32 v8, 1.0, v8
	v_rcp_f32_e32 v8, v8
	v_mul_f32_e32 v9, 0xbfb8aa3b, v9
	v_mul_f32_e32 v112, v112, v189
	v_mul_f32_e32 v112, 0x3fb8aa3b, v112
	v_exp_f32_e32 v112, v112
	v_exp_f32_e32 v9, v9
	v_add_f32_e32 v10, v10, v46
	v_mul_f32_e32 v10, 0xbfb8aa3b, v10
	v_sub_f32_e32 v116, 1.0, v112
	v_add_f32_e32 v112, 1.0, v112
	v_mul_f32_e32 v112, v116, v112
	v_max_f32_e32 v112, 0, v112
	v_sqrt_f32_e32 v112, v112
	v_add_f32_e32 v9, 1.0, v9
	v_rcp_f32_e32 v9, v9
	v_exp_f32_e32 v10, v10
	v_mul_f32_e32 v112, v113, v112
	v_mul_f32_e32 v132, v112, v132
	v_add_f32_e32 v112, v118, v30
	v_mul_f32_e32 v112, 0xbfb8aa3b, v112
	v_exp_f32_e32 v112, v112
	v_add_f32_e32 v113, v114, v34
	v_mul_f32_e32 v113, 0xbfb8aa3b, v113
	v_exp_f32_e32 v113, v113
	v_add_f32_e32 v112, 1.0, v112
	v_rcp_f32_e32 v112, v112
	v_add_f32_e32 v10, 1.0, v10
	v_add_f32_e32 v113, 1.0, v113
	v_rcp_f32_e32 v113, v113
	v_mul_f32_e32 v112, v112, v150
	v_mul_f32_e32 v112, 0x3fb8aa3b, v112
	v_exp_f32_e32 v112, v112
	v_rcp_f32_e32 v10, v10
	v_add_f32_e32 v4, v4, v28
	v_mul_f32_e32 v4, 0xbfb8aa3b, v4
	v_sub_f32_e32 v117, 1.0, v112
	v_add_f32_e32 v112, 1.0, v112
	v_mul_f32_e32 v112, v117, v112
	v_max_f32_e32 v112, 0, v112
	v_sqrt_f32_e32 v112, v112
	v_exp_f32_e32 v4, v4
	v_add_f32_e32 v11, v11, v47
	v_mul_f32_e32 v11, 0xbfb8aa3b, v11
	v_mul_f32_e32 v112, v113, v112
	v_mul_f32_e32 v118, v112, v138
	v_add_f32_e32 v112, v119, v31
	v_mul_f32_e32 v112, 0xbfb8aa3b, v112
	v_exp_f32_e32 v112, v112
	v_add_f32_e32 v113, v115, v35
	v_mul_f32_e32 v113, 0xbfb8aa3b, v113
	v_exp_f32_e32 v113, v113
	v_add_f32_e32 v112, 1.0, v112
	v_rcp_f32_e32 v112, v112
	v_add_f32_e32 v4, 1.0, v4
	v_add_f32_e32 v113, 1.0, v113
	v_rcp_f32_e32 v113, v113
	v_mul_f32_e32 v112, v112, v151
	v_mul_f32_e32 v112, 0x3fb8aa3b, v112
	v_exp_f32_e32 v112, v112
	v_rcp_f32_e32 v4, v4
	v_exp_f32_e32 v11, v11
	v_add_f32_e32 v0, v0, v32
	v_sub_f32_e32 v115, 1.0, v112
	v_add_f32_e32 v112, 1.0, v112
	v_mul_f32_e32 v112, v115, v112
	v_max_f32_e32 v112, 0, v112
	v_sqrt_f32_e32 v112, v112
	v_mul_f32_e32 v4, v4, v188
	v_add_f32_e32 v11, 1.0, v11
	v_mul_f32_e32 v4, 0x3fb8aa3b, v4
	v_mul_f32_e32 v112, v113, v112
	v_mul_f32_e32 v119, v112, v130
	v_cvt_pk_bf16_f32 v112, v133, v125
	v_cvt_pk_bf16_f32 v113, v126, v127
	v_cvt_pk_bf16_f32 v114, v124, v116
	v_cvt_pk_bf16_f32 v115, v117, v115
	v_lshl_add_u64 v[116:117], s[20:21], 0, v[128:129]
	global_store_dwordx4 v[116:117], v[112:115], off sc0 sc1
	s_nop 1
	v_cvt_pk_bf16_f32 v112, v120, v121
	v_cvt_pk_bf16_f32 v113, v122, v123
	v_cvt_pk_bf16_f32 v114, v131, v132
	v_cvt_pk_bf16_f32 v115, v118, v119
	v_lshl_add_u64 v[116:117], s[34:35], 0, v[128:129]
	global_store_dwordx4 v[116:117], v[112:115], off sc0 sc1
	s_nop 1
	v_or_b32_e32 v112, 32, v168
	v_ashrrev_i32_e32 v113, 31, v112
	v_lshlrev_b64 v[112:113], 10, v[112:113]
	v_lshl_add_u64 v[112:113], v[112:113], 0, v[166:167]
	v_lshlrev_b64 v[112:113], 1, v[112:113]
	v_lshl_add_u64 v[114:115], s[30:31], 0, v[112:113]
	global_load_dwordx4 v[114:117], v[114:115], off
	v_rcp_f32_e32 v11, v11
	v_exp_f32_e32 v4, v4
	v_mul_f32_e32 v0, 0xbfb8aa3b, v0
	v_exp_f32_e32 v0, v0
	v_add_f32_e32 v1, v1, v33
	v_mul_f32_e32 v1, 0xbfb8aa3b, v1
	v_exp_f32_e32 v1, v1
	v_add_f32_e32 v0, 1.0, v0
	v_rcp_f32_e32 v0, v0
	v_add_f32_e32 v1, 1.0, v1
	v_rcp_f32_e32 v1, v1
	s_waitcnt vmcnt(0)
	v_lshlrev_b32_e32 v118, 16, v114
	v_and_b32_e32 v119, 0xffff0000, v114
	v_lshlrev_b32_e32 v122, 16, v117
	v_and_b32_e32 v114, 0xffff0000, v117
	v_sub_f32_e32 v117, 1.0, v108
	v_add_f32_e32 v108, 1.0, v108
	v_mul_f32_e32 v108, v117, v108
	v_max_f32_e32 v108, 0, v108
	v_sqrt_f32_e32 v108, v108
	v_lshlrev_b32_e32 v120, 16, v115
	v_and_b32_e32 v115, 0xffff0000, v115
	v_lshlrev_b32_e32 v121, 16, v116
	v_mul_f32_e32 v104, v104, v108
	v_add_f32_e32 v108, v109, v41
	v_mul_f32_e32 v108, 0xbfb8aa3b, v108
	v_exp_f32_e32 v108, v108
	v_and_b32_e32 v116, 0xffff0000, v116
	v_mul_f32_e32 v104, v104, v118
	v_add_f32_e32 v108, 1.0, v108
	v_rcp_f32_e32 v108, v108
	s_nop 0
	v_mul_f32_e32 v108, v108, v190
	v_mul_f32_e32 v108, 0x3fb8aa3b, v108
	v_exp_f32_e32 v108, v108
	s_nop 0
	v_sub_f32_e32 v109, 1.0, v108
	v_add_f32_e32 v108, 1.0, v108
	v_mul_f32_e32 v108, v109, v108
	v_max_f32_e32 v108, 0, v108
	v_sqrt_f32_e32 v108, v108
	s_nop 0
	v_mul_f32_e32 v105, v105, v108
	v_add_f32_e32 v108, v110, v42
	v_mul_f32_e32 v108, 0xbfb8aa3b, v108
	v_exp_f32_e32 v108, v108
	v_mul_f32_e32 v105, v105, v119
	v_add_f32_e32 v108, 1.0, v108
	v_rcp_f32_e32 v108, v108
	s_nop 0
	v_mul_f32_e32 v108, v108, v191
	v_mul_f32_e32 v108, 0x3fb8aa3b, v108
	v_exp_f32_e32 v108, v108
	s_nop 0
	v_sub_f32_e32 v110, 1.0, v108
	v_add_f32_e32 v108, 1.0, v108
	v_mul_f32_e32 v108, v110, v108
	v_max_f32_e32 v108, 0, v108
	v_sqrt_f32_e32 v108, v108
	s_nop 0
	v_mul_f32_e32 v106, v106, v108
	v_add_f32_e32 v108, v111, v43
	v_mul_f32_e32 v108, 0xbfb8aa3b, v108
	v_exp_f32_e32 v108, v108
	v_mul_f32_e32 v106, v106, v120
	v_add_f32_e32 v108, 1.0, v108
	v_rcp_f32_e32 v108, v108
	s_nop 0
	v_mul_f32_e32 v108, v108, v192
	v_mul_f32_e32 v108, 0x3fb8aa3b, v108
	v_exp_f32_e32 v108, v108
	s_nop 0
	v_sub_f32_e32 v111, 1.0, v108
	v_add_f32_e32 v108, 1.0, v108
	v_mul_f32_e32 v108, v111, v108
	v_max_f32_e32 v108, 0, v108
	v_sqrt_f32_e32 v108, v108
	s_nop 0
	v_mul_f32_e32 v107, v107, v108
	v_sub_f32_e32 v108, 1.0, v100
	v_add_f32_e32 v100, 1.0, v100
	v_mul_f32_e32 v100, v108, v100
	v_max_f32_e32 v100, 0, v100
	v_sqrt_f32_e32 v100, v100
	v_mul_f32_e32 v107, v107, v115
	v_mul_f32_e32 v96, v96, v100
	v_mul_f32_e32 v115, v96, v121
	v_add_f32_e32 v96, v101, v29
	v_mul_f32_e32 v96, 0xbfb8aa3b, v96
	v_exp_f32_e32 v96, v96
	s_nop 0
	v_add_f32_e32 v96, 1.0, v96
	v_rcp_f32_e32 v96, v96
	s_nop 0
	v_mul_f32_e32 v96, v96, v189
	v_mul_f32_e32 v96, 0x3fb8aa3b, v96
	v_exp_f32_e32 v96, v96
	s_nop 0
	v_sub_f32_e32 v100, 1.0, v96
	v_add_f32_e32 v96, 1.0, v96
	v_mul_f32_e32 v96, v100, v96
	v_max_f32_e32 v96, 0, v96
	v_sqrt_f32_e32 v96, v96
	s_nop 0
	v_mul_f32_e32 v96, v97, v96
	v_mul_f32_e32 v116, v96, v116
	v_add_f32_e32 v96, v102, v30
	v_mul_f32_e32 v96, 0xbfb8aa3b, v96
	v_exp_f32_e32 v96, v96
	v_add_f32_e32 v97, v98, v34
	v_mul_f32_e32 v97, 0xbfb8aa3b, v97
	v_exp_f32_e32 v97, v97
	v_add_f32_e32 v96, 1.0, v96
	v_rcp_f32_e32 v96, v96
	v_add_f32_e32 v97, 1.0, v97
	v_rcp_f32_e32 v97, v97
	v_mul_f32_e32 v96, v96, v150
	v_mul_f32_e32 v96, 0x3fb8aa3b, v96
	v_exp_f32_e32 v96, v96
	s_nop 0
	v_sub_f32_e32 v101, 1.0, v96
	v_add_f32_e32 v96, 1.0, v96
	v_mul_f32_e32 v96, v101, v96
	v_max_f32_e32 v96, 0, v96
	v_sqrt_f32_e32 v96, v96
	s_nop 0
	v_mul_f32_e32 v96, v97, v96
	v_mul_f32_e32 v102, v96, v122
	v_add_f32_e32 v96, v103, v31
	v_mul_f32_e32 v96, 0xbfb8aa3b, v96
	v_exp_f32_e32 v96, v96
	v_add_f32_e32 v97, v99, v35
	v_mul_f32_e32 v97, 0xbfb8aa3b, v97
	v_exp_f32_e32 v97, v97
	v_add_f32_e32 v96, 1.0, v96
	v_rcp_f32_e32 v96, v96
	v_add_f32_e32 v97, 1.0, v97
	v_rcp_f32_e32 v97, v97
	v_mul_f32_e32 v96, v96, v151
	v_mul_f32_e32 v96, 0x3fb8aa3b, v96
	v_exp_f32_e32 v96, v96
	s_nop 0
	v_sub_f32_e32 v99, 1.0, v96
	v_add_f32_e32 v96, 1.0, v96
	v_mul_f32_e32 v96, v99, v96
	v_max_f32_e32 v96, 0, v96
	v_sqrt_f32_e32 v96, v96
	s_nop 0
	v_mul_f32_e32 v96, v97, v96
	v_mul_f32_e32 v103, v96, v114
	v_cvt_pk_bf16_f32 v96, v117, v109
	v_cvt_pk_bf16_f32 v97, v110, v111
	v_cvt_pk_bf16_f32 v98, v108, v100
	v_cvt_pk_bf16_f32 v99, v101, v99
	v_lshl_add_u64 v[100:101], s[20:21], 0, v[112:113]
	global_store_dwordx4 v[100:101], v[96:99], off sc0 sc1
	s_nop 1
	v_cvt_pk_bf16_f32 v96, v104, v105
	v_cvt_pk_bf16_f32 v97, v106, v107
	v_cvt_pk_bf16_f32 v98, v115, v116
	v_cvt_pk_bf16_f32 v99, v102, v103
	v_lshl_add_u64 v[100:101], s[34:35], 0, v[112:113]
	global_store_dwordx4 v[100:101], v[96:99], off sc0 sc1
	s_nop 1
	v_or_b32_e32 v96, 48, v168
	v_ashrrev_i32_e32 v97, 31, v96
	v_lshlrev_b64 v[96:97], 10, v[96:97]
	v_lshl_add_u64 v[96:97], v[96:97], 0, v[166:167]
	v_lshlrev_b64 v[96:97], 1, v[96:97]
	v_lshl_add_u64 v[98:99], s[30:31], 0, v[96:97]
	global_load_dwordx4 v[98:101], v[98:99], off
	s_waitcnt vmcnt(0)
	v_lshlrev_b32_e32 v102, 16, v98
	v_and_b32_e32 v103, 0xffff0000, v98
	v_lshlrev_b32_e32 v106, 16, v101
	v_and_b32_e32 v98, 0xffff0000, v101
	v_sub_f32_e32 v101, 1.0, v92
	v_add_f32_e32 v92, 1.0, v92
	v_mul_f32_e32 v92, v101, v92
	v_max_f32_e32 v92, 0, v92
	v_sqrt_f32_e32 v92, v92
	v_lshlrev_b32_e32 v104, 16, v99
	v_and_b32_e32 v99, 0xffff0000, v99
	v_lshlrev_b32_e32 v105, 16, v100
	v_mul_f32_e32 v88, v88, v92
	v_add_f32_e32 v92, v93, v41
	v_mul_f32_e32 v92, 0xbfb8aa3b, v92
	v_exp_f32_e32 v92, v92
	v_and_b32_e32 v100, 0xffff0000, v100
	v_mul_f32_e32 v88, v88, v102
	v_add_f32_e32 v92, 1.0, v92
	v_rcp_f32_e32 v92, v92
	s_nop 0
	v_mul_f32_e32 v92, v92, v190
	v_mul_f32_e32 v92, 0x3fb8aa3b, v92
	v_exp_f32_e32 v92, v92
	s_nop 0
	v_sub_f32_e32 v93, 1.0, v92
	v_add_f32_e32 v92, 1.0, v92
	v_mul_f32_e32 v92, v93, v92
	v_max_f32_e32 v92, 0, v92
	v_sqrt_f32_e32 v92, v92
	s_nop 0
	v_mul_f32_e32 v89, v89, v92
	v_add_f32_e32 v92, v94, v42
	v_mul_f32_e32 v92, 0xbfb8aa3b, v92
	v_exp_f32_e32 v92, v92
	v_mul_f32_e32 v89, v89, v103
	v_add_f32_e32 v92, 1.0, v92
	v_rcp_f32_e32 v92, v92
	s_nop 0
	v_mul_f32_e32 v92, v92, v191
	v_mul_f32_e32 v92, 0x3fb8aa3b, v92
	v_exp_f32_e32 v92, v92
	s_nop 0
	v_sub_f32_e32 v94, 1.0, v92
	v_add_f32_e32 v92, 1.0, v92
	v_mul_f32_e32 v92, v94, v92
	v_max_f32_e32 v92, 0, v92
	v_sqrt_f32_e32 v92, v92
	s_nop 0
	v_mul_f32_e32 v90, v90, v92
	v_add_f32_e32 v92, v95, v43
	v_mul_f32_e32 v92, 0xbfb8aa3b, v92
	v_exp_f32_e32 v92, v92
	v_mul_f32_e32 v90, v90, v104
	v_add_f32_e32 v92, 1.0, v92
	v_rcp_f32_e32 v92, v92
	s_nop 0
	v_mul_f32_e32 v92, v92, v192
	v_mul_f32_e32 v92, 0x3fb8aa3b, v92
	v_exp_f32_e32 v92, v92
	s_nop 0
	v_sub_f32_e32 v95, 1.0, v92
	v_add_f32_e32 v92, 1.0, v92
	v_mul_f32_e32 v92, v95, v92
	v_max_f32_e32 v92, 0, v92
	v_sqrt_f32_e32 v92, v92
	s_nop 0
	v_mul_f32_e32 v91, v91, v92
	v_sub_f32_e32 v92, 1.0, v84
	v_add_f32_e32 v84, 1.0, v84
	v_mul_f32_e32 v84, v92, v84
	v_max_f32_e32 v84, 0, v84
	v_sqrt_f32_e32 v84, v84
	v_mul_f32_e32 v91, v91, v99
	v_mul_f32_e32 v80, v80, v84
	v_mul_f32_e32 v99, v80, v105
	v_add_f32_e32 v80, v85, v29
	v_mul_f32_e32 v80, 0xbfb8aa3b, v80
	v_exp_f32_e32 v80, v80
	s_nop 0
	v_add_f32_e32 v80, 1.0, v80
	v_rcp_f32_e32 v80, v80
	s_nop 0
	v_mul_f32_e32 v80, v80, v189
	v_mul_f32_e32 v80, 0x3fb8aa3b, v80
	v_exp_f32_e32 v80, v80
	s_nop 0
	v_sub_f32_e32 v84, 1.0, v80
	v_add_f32_e32 v80, 1.0, v80
	v_mul_f32_e32 v80, v84, v80
	v_max_f32_e32 v80, 0, v80
	v_sqrt_f32_e32 v80, v80
	s_nop 0
	v_mul_f32_e32 v80, v81, v80
	v_mul_f32_e32 v100, v80, v100
	v_add_f32_e32 v80, v86, v30
	v_mul_f32_e32 v80, 0xbfb8aa3b, v80
	v_exp_f32_e32 v80, v80
	v_add_f32_e32 v81, v82, v34
	v_mul_f32_e32 v81, 0xbfb8aa3b, v81
	v_exp_f32_e32 v81, v81
	v_add_f32_e32 v80, 1.0, v80
	v_rcp_f32_e32 v80, v80
	v_add_f32_e32 v81, 1.0, v81
	v_rcp_f32_e32 v81, v81
	v_mul_f32_e32 v80, v80, v150
	v_mul_f32_e32 v80, 0x3fb8aa3b, v80
	v_exp_f32_e32 v80, v80
	s_nop 0
	v_sub_f32_e32 v85, 1.0, v80
	v_add_f32_e32 v80, 1.0, v80
	v_mul_f32_e32 v80, v85, v80
	v_max_f32_e32 v80, 0, v80
	v_sqrt_f32_e32 v80, v80
	s_nop 0
	v_mul_f32_e32 v80, v81, v80
	v_mul_f32_e32 v86, v80, v106
	v_add_f32_e32 v80, v87, v31
	v_mul_f32_e32 v80, 0xbfb8aa3b, v80
	v_exp_f32_e32 v80, v80
	v_add_f32_e32 v81, v83, v35
	v_mul_f32_e32 v81, 0xbfb8aa3b, v81
	v_exp_f32_e32 v81, v81
	v_add_f32_e32 v80, 1.0, v80
	v_rcp_f32_e32 v80, v80
	v_add_f32_e32 v81, 1.0, v81
	v_rcp_f32_e32 v81, v81
	v_mul_f32_e32 v80, v80, v151
	v_mul_f32_e32 v80, 0x3fb8aa3b, v80
	v_exp_f32_e32 v80, v80
	s_nop 0
	v_sub_f32_e32 v83, 1.0, v80
	v_add_f32_e32 v80, 1.0, v80
	v_mul_f32_e32 v80, v83, v80
	v_max_f32_e32 v80, 0, v80
	v_sqrt_f32_e32 v80, v80
	s_nop 0
	v_mul_f32_e32 v80, v81, v80
	v_mul_f32_e32 v87, v80, v98
	v_cvt_pk_bf16_f32 v80, v101, v93
	v_cvt_pk_bf16_f32 v81, v94, v95
	v_cvt_pk_bf16_f32 v82, v92, v84
	v_cvt_pk_bf16_f32 v83, v85, v83
	v_lshl_add_u64 v[84:85], s[20:21], 0, v[96:97]
	global_store_dwordx4 v[84:85], v[80:83], off sc0 sc1
	s_nop 1
	v_cvt_pk_bf16_f32 v80, v88, v89
	v_cvt_pk_bf16_f32 v81, v90, v91
	v_cvt_pk_bf16_f32 v82, v99, v100
	v_cvt_pk_bf16_f32 v83, v86, v87
	v_lshl_add_u64 v[84:85], s[34:35], 0, v[96:97]
	global_store_dwordx4 v[84:85], v[80:83], off sc0 sc1
	s_nop 1
	v_lshl_add_u64 v[80:81], v[148:149], 0, s[8:9]
	v_lshl_add_u64 v[82:83], s[30:31], 0, v[80:81]
	global_load_dwordx4 v[82:85], v[82:83], off
	s_mov_b64 s[8:9], 0x48000
	s_waitcnt vmcnt(0)
	v_lshlrev_b32_e32 v86, 16, v82
	v_and_b32_e32 v87, 0xffff0000, v82
	v_lshlrev_b32_e32 v90, 16, v85
	v_and_b32_e32 v82, 0xffff0000, v85
	v_sub_f32_e32 v85, 1.0, v76
	v_add_f32_e32 v76, 1.0, v76
	v_mul_f32_e32 v76, v85, v76
	v_max_f32_e32 v76, 0, v76
	v_sqrt_f32_e32 v76, v76
	v_lshlrev_b32_e32 v88, 16, v83
	v_and_b32_e32 v83, 0xffff0000, v83
	v_lshlrev_b32_e32 v89, 16, v84
	v_mul_f32_e32 v72, v72, v76
	v_add_f32_e32 v76, v77, v41
	v_mul_f32_e32 v76, 0xbfb8aa3b, v76
	v_exp_f32_e32 v76, v76
	v_and_b32_e32 v84, 0xffff0000, v84
	v_mul_f32_e32 v72, v72, v86
	v_add_f32_e32 v76, 1.0, v76
	v_rcp_f32_e32 v76, v76
	s_nop 0
	v_mul_f32_e32 v76, v76, v190
	v_mul_f32_e32 v76, 0x3fb8aa3b, v76
	v_exp_f32_e32 v76, v76
	s_nop 0
	v_sub_f32_e32 v77, 1.0, v76
	v_add_f32_e32 v76, 1.0, v76
	v_mul_f32_e32 v76, v77, v76
	v_max_f32_e32 v76, 0, v76
	v_sqrt_f32_e32 v76, v76
	s_nop 0
	v_mul_f32_e32 v73, v73, v76
	v_add_f32_e32 v76, v78, v42
	v_mul_f32_e32 v76, 0xbfb8aa3b, v76
	v_exp_f32_e32 v76, v76
	v_mul_f32_e32 v73, v73, v87
	v_add_f32_e32 v76, 1.0, v76
	v_rcp_f32_e32 v76, v76
	s_nop 0
	v_mul_f32_e32 v76, v76, v191
	v_mul_f32_e32 v76, 0x3fb8aa3b, v76
	v_exp_f32_e32 v76, v76
	s_nop 0
	v_sub_f32_e32 v78, 1.0, v76
	v_add_f32_e32 v76, 1.0, v76
	v_mul_f32_e32 v76, v78, v76
	v_max_f32_e32 v76, 0, v76
	v_sqrt_f32_e32 v76, v76
	s_nop 0
	v_mul_f32_e32 v74, v74, v76
	v_add_f32_e32 v76, v79, v43
	v_mul_f32_e32 v76, 0xbfb8aa3b, v76
	v_exp_f32_e32 v76, v76
	v_mul_f32_e32 v74, v74, v88
	v_add_f32_e32 v76, 1.0, v76
	v_rcp_f32_e32 v76, v76
	s_nop 0
	v_mul_f32_e32 v76, v76, v192
	v_mul_f32_e32 v76, 0x3fb8aa3b, v76
	v_exp_f32_e32 v76, v76
	s_nop 0
	v_sub_f32_e32 v79, 1.0, v76
	v_add_f32_e32 v76, 1.0, v76
	v_mul_f32_e32 v76, v79, v76
	v_max_f32_e32 v76, 0, v76
	v_sqrt_f32_e32 v76, v76
	s_nop 0
	v_mul_f32_e32 v75, v75, v76
	v_sub_f32_e32 v76, 1.0, v68
	v_add_f32_e32 v68, 1.0, v68
	v_mul_f32_e32 v68, v76, v68
	v_max_f32_e32 v68, 0, v68
	v_sqrt_f32_e32 v68, v68
	v_mul_f32_e32 v75, v75, v83
	v_mul_f32_e32 v64, v64, v68
	v_mul_f32_e32 v83, v64, v89
	v_add_f32_e32 v64, v69, v29
	v_mul_f32_e32 v64, 0xbfb8aa3b, v64
	v_exp_f32_e32 v64, v64
	s_nop 0
	v_add_f32_e32 v64, 1.0, v64
	v_rcp_f32_e32 v64, v64
	s_nop 0
	v_mul_f32_e32 v64, v64, v189
	v_mul_f32_e32 v64, 0x3fb8aa3b, v64
	v_exp_f32_e32 v64, v64
	s_nop 0
	v_sub_f32_e32 v68, 1.0, v64
	v_add_f32_e32 v64, 1.0, v64
	v_mul_f32_e32 v64, v68, v64
	v_max_f32_e32 v64, 0, v64
	v_sqrt_f32_e32 v64, v64
	s_nop 0
	v_mul_f32_e32 v64, v65, v64
	v_mul_f32_e32 v84, v64, v84
	v_add_f32_e32 v64, v70, v30
	v_mul_f32_e32 v64, 0xbfb8aa3b, v64
	v_exp_f32_e32 v64, v64
	v_add_f32_e32 v65, v66, v34
	v_mul_f32_e32 v65, 0xbfb8aa3b, v65
	v_exp_f32_e32 v65, v65
	v_add_f32_e32 v64, 1.0, v64
	v_rcp_f32_e32 v64, v64
	v_add_f32_e32 v65, 1.0, v65
	v_rcp_f32_e32 v65, v65
	v_mul_f32_e32 v64, v64, v150
	v_mul_f32_e32 v64, 0x3fb8aa3b, v64
	v_exp_f32_e32 v64, v64
	s_nop 0
	v_sub_f32_e32 v69, 1.0, v64
	v_add_f32_e32 v64, 1.0, v64
	v_mul_f32_e32 v64, v69, v64
	v_max_f32_e32 v64, 0, v64
	v_sqrt_f32_e32 v64, v64
	s_nop 0
	v_mul_f32_e32 v64, v65, v64
	v_mul_f32_e32 v70, v64, v90
	v_add_f32_e32 v64, v71, v31
	v_mul_f32_e32 v64, 0xbfb8aa3b, v64
	v_exp_f32_e32 v64, v64
	v_add_f32_e32 v65, v67, v35
	v_mul_f32_e32 v65, 0xbfb8aa3b, v65
	v_exp_f32_e32 v65, v65
	v_add_f32_e32 v64, 1.0, v64
	v_rcp_f32_e32 v64, v64
	v_add_f32_e32 v65, 1.0, v65
	v_rcp_f32_e32 v65, v65
	v_mul_f32_e32 v64, v64, v151
	v_mul_f32_e32 v64, 0x3fb8aa3b, v64
	v_exp_f32_e32 v64, v64
	s_nop 0
	v_sub_f32_e32 v67, 1.0, v64
	v_add_f32_e32 v64, 1.0, v64
	v_mul_f32_e32 v64, v67, v64
	v_max_f32_e32 v64, 0, v64
	v_sqrt_f32_e32 v64, v64
	s_nop 0
	v_mul_f32_e32 v64, v65, v64
	v_mul_f32_e32 v71, v64, v82
	v_cvt_pk_bf16_f32 v64, v85, v77
	v_cvt_pk_bf16_f32 v65, v78, v79
	v_cvt_pk_bf16_f32 v66, v76, v68
	v_cvt_pk_bf16_f32 v67, v69, v67
	v_lshl_add_u64 v[68:69], s[20:21], 0, v[80:81]
	global_store_dwordx4 v[68:69], v[64:67], off sc0 sc1
	s_nop 1
	v_cvt_pk_bf16_f32 v64, v72, v73
	v_cvt_pk_bf16_f32 v65, v74, v75
	v_cvt_pk_bf16_f32 v66, v83, v84
	v_cvt_pk_bf16_f32 v67, v70, v71
	v_lshl_add_u64 v[68:69], s[34:35], 0, v[80:81]
	global_store_dwordx4 v[68:69], v[64:67], off sc0 sc1
	s_nop 1
	v_lshl_add_u64 v[64:65], v[148:149], 0, s[8:9]
	v_lshl_add_u64 v[66:67], s[30:31], 0, v[64:65]
	global_load_dwordx4 v[66:69], v[66:67], off
	s_mov_b64 s[8:9], 0x50000
	s_waitcnt vmcnt(0)
	v_lshlrev_b32_e32 v70, 16, v66
	v_and_b32_e32 v71, 0xffff0000, v66
	v_lshlrev_b32_e32 v74, 16, v69
	v_and_b32_e32 v66, 0xffff0000, v69
	v_sub_f32_e32 v69, 1.0, v60
	v_add_f32_e32 v60, 1.0, v60
	v_mul_f32_e32 v60, v69, v60
	v_max_f32_e32 v60, 0, v60
	v_sqrt_f32_e32 v60, v60
	v_lshlrev_b32_e32 v72, 16, v67
	v_and_b32_e32 v67, 0xffff0000, v67
	v_lshlrev_b32_e32 v73, 16, v68
	v_mul_f32_e32 v56, v56, v60
	v_add_f32_e32 v60, v61, v41
	v_mul_f32_e32 v60, 0xbfb8aa3b, v60
	v_exp_f32_e32 v60, v60
	v_and_b32_e32 v68, 0xffff0000, v68
	v_mul_f32_e32 v56, v56, v70
	v_add_f32_e32 v60, 1.0, v60
	v_rcp_f32_e32 v60, v60
	s_nop 0
	v_mul_f32_e32 v60, v60, v190
	v_mul_f32_e32 v60, 0x3fb8aa3b, v60
	v_exp_f32_e32 v60, v60
	s_nop 0
	v_sub_f32_e32 v61, 1.0, v60
	v_add_f32_e32 v60, 1.0, v60
	v_mul_f32_e32 v60, v61, v60
	v_max_f32_e32 v60, 0, v60
	v_sqrt_f32_e32 v60, v60
	s_nop 0
	v_mul_f32_e32 v57, v57, v60
	v_add_f32_e32 v60, v62, v42
	v_mul_f32_e32 v60, 0xbfb8aa3b, v60
	v_exp_f32_e32 v60, v60
	v_mul_f32_e32 v57, v57, v71
	v_add_f32_e32 v60, 1.0, v60
	v_rcp_f32_e32 v60, v60
	s_nop 0
	v_mul_f32_e32 v60, v60, v191
	v_mul_f32_e32 v60, 0x3fb8aa3b, v60
	v_exp_f32_e32 v60, v60
	s_nop 0
	v_sub_f32_e32 v62, 1.0, v60
	v_add_f32_e32 v60, 1.0, v60
	v_mul_f32_e32 v60, v62, v60
	v_max_f32_e32 v60, 0, v60
	v_sqrt_f32_e32 v60, v60
	s_nop 0
	v_mul_f32_e32 v58, v58, v60
	v_add_f32_e32 v60, v63, v43
	v_mul_f32_e32 v60, 0xbfb8aa3b, v60
	v_exp_f32_e32 v60, v60
	v_mul_f32_e32 v58, v58, v72
	v_add_f32_e32 v60, 1.0, v60
	v_rcp_f32_e32 v60, v60
	s_nop 0
	v_mul_f32_e32 v60, v60, v192
	v_mul_f32_e32 v60, 0x3fb8aa3b, v60
	v_exp_f32_e32 v60, v60
	s_nop 0
	v_sub_f32_e32 v63, 1.0, v60
	v_add_f32_e32 v60, 1.0, v60
	v_mul_f32_e32 v60, v63, v60
	v_max_f32_e32 v60, 0, v60
	v_sqrt_f32_e32 v60, v60
	s_nop 0
	v_mul_f32_e32 v59, v59, v60
	v_sub_f32_e32 v60, 1.0, v52
	v_add_f32_e32 v52, 1.0, v52
	v_mul_f32_e32 v52, v60, v52
	v_max_f32_e32 v52, 0, v52
	v_sqrt_f32_e32 v52, v52
	v_mul_f32_e32 v59, v59, v67
	v_mul_f32_e32 v48, v48, v52
	v_mul_f32_e32 v67, v48, v73
	v_add_f32_e32 v48, v53, v29
	v_mul_f32_e32 v48, 0xbfb8aa3b, v48
	v_exp_f32_e32 v48, v48
	s_nop 0
	v_add_f32_e32 v48, 1.0, v48
	v_rcp_f32_e32 v48, v48
	s_nop 0
	v_mul_f32_e32 v48, v48, v189
	v_mul_f32_e32 v48, 0x3fb8aa3b, v48
	v_exp_f32_e32 v48, v48
	s_nop 0
	v_sub_f32_e32 v52, 1.0, v48
	v_add_f32_e32 v48, 1.0, v48
	v_mul_f32_e32 v48, v52, v48
	v_max_f32_e32 v48, 0, v48
	v_sqrt_f32_e32 v48, v48
	s_nop 0
	v_mul_f32_e32 v48, v49, v48
	v_mul_f32_e32 v68, v48, v68
	v_add_f32_e32 v48, v54, v30
	v_mul_f32_e32 v48, 0xbfb8aa3b, v48
	v_exp_f32_e32 v48, v48
	v_add_f32_e32 v49, v50, v34
	v_mul_f32_e32 v49, 0xbfb8aa3b, v49
	v_exp_f32_e32 v49, v49
	v_add_f32_e32 v48, 1.0, v48
	v_rcp_f32_e32 v48, v48
	v_add_f32_e32 v49, 1.0, v49
	v_rcp_f32_e32 v49, v49
	v_mul_f32_e32 v48, v48, v150
	v_mul_f32_e32 v48, 0x3fb8aa3b, v48
	v_exp_f32_e32 v48, v48
	s_nop 0
	v_sub_f32_e32 v53, 1.0, v48
	v_add_f32_e32 v48, 1.0, v48
	v_mul_f32_e32 v48, v53, v48
	v_max_f32_e32 v48, 0, v48
	v_sqrt_f32_e32 v48, v48
	s_nop 0
	v_mul_f32_e32 v48, v49, v48
	v_mul_f32_e32 v54, v48, v74
	v_add_f32_e32 v48, v55, v31
	v_mul_f32_e32 v48, 0xbfb8aa3b, v48
	v_exp_f32_e32 v48, v48
	v_add_f32_e32 v49, v51, v35
	v_mul_f32_e32 v49, 0xbfb8aa3b, v49
	v_exp_f32_e32 v49, v49
	v_add_f32_e32 v48, 1.0, v48
	v_rcp_f32_e32 v48, v48
	v_add_f32_e32 v49, 1.0, v49
	v_rcp_f32_e32 v49, v49
	v_mul_f32_e32 v48, v48, v151
	v_mul_f32_e32 v48, 0x3fb8aa3b, v48
	v_exp_f32_e32 v48, v48
	s_nop 0
	v_sub_f32_e32 v51, 1.0, v48
	v_add_f32_e32 v48, 1.0, v48
	v_mul_f32_e32 v48, v51, v48
	v_max_f32_e32 v48, 0, v48
	v_sqrt_f32_e32 v48, v48
	s_nop 0
	v_mul_f32_e32 v48, v49, v48
	v_mul_f32_e32 v55, v48, v66
	v_cvt_pk_bf16_f32 v48, v69, v61
	v_cvt_pk_bf16_f32 v49, v62, v63
	v_cvt_pk_bf16_f32 v50, v60, v52
	v_cvt_pk_bf16_f32 v51, v53, v51
	v_lshl_add_u64 v[52:53], s[20:21], 0, v[64:65]
	global_store_dwordx4 v[52:53], v[48:51], off sc0 sc1
	s_nop 1
	v_cvt_pk_bf16_f32 v48, v56, v57
	v_cvt_pk_bf16_f32 v49, v58, v59
	v_cvt_pk_bf16_f32 v50, v67, v68
	v_cvt_pk_bf16_f32 v51, v54, v55
	v_lshl_add_u64 v[52:53], s[34:35], 0, v[64:65]
	global_store_dwordx4 v[52:53], v[48:51], off sc0 sc1
	s_nop 1
	v_lshl_add_u64 v[48:49], v[148:149], 0, s[8:9]
	v_lshl_add_u64 v[50:51], s[30:31], 0, v[48:49]
	global_load_dwordx4 v[50:53], v[50:51], off
	s_mov_b64 s[8:9], 0x58000
	s_waitcnt vmcnt(0)
	v_lshlrev_b32_e32 v54, 16, v50
	v_and_b32_e32 v55, 0xffff0000, v50
	v_lshlrev_b32_e32 v58, 16, v53
	v_and_b32_e32 v50, 0xffff0000, v53
	v_sub_f32_e32 v53, 1.0, v36
	v_add_f32_e32 v36, 1.0, v36
	v_mul_f32_e32 v36, v53, v36
	v_max_f32_e32 v36, 0, v36
	v_sqrt_f32_e32 v36, v36
	v_lshlrev_b32_e32 v56, 16, v51
	v_and_b32_e32 v51, 0xffff0000, v51
	v_lshlrev_b32_e32 v57, 16, v52
	v_mul_f32_e32 v24, v24, v36
	v_add_f32_e32 v36, v37, v41
	v_mul_f32_e32 v36, 0xbfb8aa3b, v36
	v_exp_f32_e32 v36, v36
	v_and_b32_e32 v52, 0xffff0000, v52
	v_mul_f32_e32 v24, v24, v54
	v_add_f32_e32 v36, 1.0, v36
	v_rcp_f32_e32 v36, v36
	s_nop 0
	v_mul_f32_e32 v36, v36, v190
	v_mul_f32_e32 v36, 0x3fb8aa3b, v36
	v_exp_f32_e32 v36, v36
	s_nop 0
	v_sub_f32_e32 v37, 1.0, v36
	v_add_f32_e32 v36, 1.0, v36
	v_mul_f32_e32 v36, v37, v36
	v_max_f32_e32 v36, 0, v36
	v_sqrt_f32_e32 v36, v36
	s_nop 0
	v_mul_f32_e32 v25, v25, v36
	v_add_f32_e32 v36, v38, v42
	v_mul_f32_e32 v36, 0xbfb8aa3b, v36
	v_exp_f32_e32 v36, v36
	v_mul_f32_e32 v25, v25, v55
	v_add_f32_e32 v36, 1.0, v36
	v_rcp_f32_e32 v36, v36
	s_nop 0
	v_mul_f32_e32 v36, v36, v191
	v_mul_f32_e32 v36, 0x3fb8aa3b, v36
	v_exp_f32_e32 v36, v36
	s_nop 0
	v_sub_f32_e32 v38, 1.0, v36
	v_add_f32_e32 v36, 1.0, v36
	v_mul_f32_e32 v36, v38, v36
	v_max_f32_e32 v36, 0, v36
	v_sqrt_f32_e32 v36, v36
	s_nop 0
	v_mul_f32_e32 v26, v26, v36
	v_add_f32_e32 v36, v39, v43
	v_mul_f32_e32 v36, 0xbfb8aa3b, v36
	v_exp_f32_e32 v36, v36
	v_mul_f32_e32 v26, v26, v56
	v_add_f32_e32 v36, 1.0, v36
	v_rcp_f32_e32 v36, v36
	s_nop 0
	v_mul_f32_e32 v36, v36, v192
	v_mul_f32_e32 v36, 0x3fb8aa3b, v36
	v_exp_f32_e32 v36, v36
	s_nop 0
	v_sub_f32_e32 v39, 1.0, v36
	v_add_f32_e32 v36, 1.0, v36
	v_mul_f32_e32 v36, v39, v36
	v_max_f32_e32 v36, 0, v36
	v_sqrt_f32_e32 v36, v36
	s_nop 0
	v_mul_f32_e32 v27, v27, v36
	v_sub_f32_e32 v36, 1.0, v20
	v_add_f32_e32 v20, 1.0, v20
	v_mul_f32_e32 v20, v36, v20
	v_max_f32_e32 v20, 0, v20
	v_sqrt_f32_e32 v20, v20
	v_mul_f32_e32 v27, v27, v51
	v_mul_f32_e32 v16, v16, v20
	v_mul_f32_e32 v51, v16, v57
	v_add_f32_e32 v16, v21, v29
	v_mul_f32_e32 v16, 0xbfb8aa3b, v16
	v_exp_f32_e32 v16, v16
	s_nop 0
	v_add_f32_e32 v16, 1.0, v16
	v_rcp_f32_e32 v16, v16
	s_nop 0
	v_mul_f32_e32 v16, v16, v189
	v_mul_f32_e32 v16, 0x3fb8aa3b, v16
	v_exp_f32_e32 v16, v16
	s_nop 0
	v_sub_f32_e32 v20, 1.0, v16
	v_add_f32_e32 v16, 1.0, v16
	v_mul_f32_e32 v16, v20, v16
	v_max_f32_e32 v16, 0, v16
	v_sqrt_f32_e32 v16, v16
	s_nop 0
	v_mul_f32_e32 v16, v17, v16
	v_mul_f32_e32 v52, v16, v52
	v_add_f32_e32 v16, v22, v30
	v_mul_f32_e32 v16, 0xbfb8aa3b, v16
	v_exp_f32_e32 v16, v16
	v_add_f32_e32 v17, v18, v34
	v_mul_f32_e32 v17, 0xbfb8aa3b, v17
	v_exp_f32_e32 v17, v17
	v_add_f32_e32 v16, 1.0, v16
	v_rcp_f32_e32 v16, v16
	v_add_f32_e32 v17, 1.0, v17
	v_rcp_f32_e32 v17, v17
	v_mul_f32_e32 v16, v16, v150
	v_mul_f32_e32 v16, 0x3fb8aa3b, v16
	v_exp_f32_e32 v16, v16
	s_nop 0
	v_sub_f32_e32 v21, 1.0, v16
	v_add_f32_e32 v16, 1.0, v16
	v_mul_f32_e32 v16, v21, v16
	v_max_f32_e32 v16, 0, v16
	v_sqrt_f32_e32 v16, v16
	s_nop 0
	v_mul_f32_e32 v16, v17, v16
	v_mul_f32_e32 v22, v16, v58
	v_add_f32_e32 v16, v23, v31
	v_mul_f32_e32 v16, 0xbfb8aa3b, v16
	v_exp_f32_e32 v16, v16
	v_add_f32_e32 v17, v19, v35
	v_mul_f32_e32 v17, 0xbfb8aa3b, v17
	v_exp_f32_e32 v17, v17
	v_add_f32_e32 v16, 1.0, v16
	v_rcp_f32_e32 v16, v16
	v_add_f32_e32 v17, 1.0, v17
	v_rcp_f32_e32 v17, v17
	v_mul_f32_e32 v16, v16, v151
	v_mul_f32_e32 v16, 0x3fb8aa3b, v16
	v_exp_f32_e32 v16, v16
	s_nop 0
	v_sub_f32_e32 v19, 1.0, v16
	v_add_f32_e32 v16, 1.0, v16
	v_mul_f32_e32 v16, v19, v16
	v_max_f32_e32 v16, 0, v16
	v_sqrt_f32_e32 v16, v16
	s_nop 0
	v_mul_f32_e32 v16, v17, v16
	v_mul_f32_e32 v23, v16, v50
	v_cvt_pk_bf16_f32 v16, v53, v37
	v_cvt_pk_bf16_f32 v17, v38, v39
	v_cvt_pk_bf16_f32 v18, v36, v20
	v_cvt_pk_bf16_f32 v19, v21, v19
	v_lshl_add_u64 v[20:21], s[20:21], 0, v[48:49]
	global_store_dwordx4 v[20:21], v[16:19], off sc0 sc1
	s_nop 1
	v_cvt_pk_bf16_f32 v16, v24, v25
	v_cvt_pk_bf16_f32 v17, v26, v27
	v_cvt_pk_bf16_f32 v18, v51, v52
	v_cvt_pk_bf16_f32 v19, v22, v23
	v_lshl_add_u64 v[20:21], s[34:35], 0, v[48:49]
	global_store_dwordx4 v[20:21], v[16:19], off sc0 sc1
	s_nop 1
	v_lshl_add_u64 v[16:17], v[148:149], 0, s[8:9]
	v_lshl_add_u64 v[18:19], s[30:31], 0, v[16:17]
	global_load_dwordx4 v[18:21], v[18:19], off
	s_waitcnt vmcnt(0)
	v_lshlrev_b32_e32 v22, 16, v18
	v_and_b32_e32 v23, 0xffff0000, v18
	v_lshlrev_b32_e32 v26, 16, v21
	v_and_b32_e32 v18, 0xffff0000, v21
	v_sub_f32_e32 v21, 1.0, v12
	v_add_f32_e32 v12, 1.0, v12
	v_mul_f32_e32 v12, v21, v12
	v_max_f32_e32 v12, 0, v12
	v_sqrt_f32_e32 v12, v12
	v_lshlrev_b32_e32 v24, 16, v19
	v_and_b32_e32 v19, 0xffff0000, v19
	v_lshlrev_b32_e32 v25, 16, v20
	v_mul_f32_e32 v8, v8, v12
	v_add_f32_e32 v12, v13, v41
	v_mul_f32_e32 v12, 0xbfb8aa3b, v12
	v_exp_f32_e32 v12, v12
	v_and_b32_e32 v20, 0xffff0000, v20
	v_mul_f32_e32 v8, v8, v22
	v_add_f32_e32 v12, 1.0, v12
	v_rcp_f32_e32 v12, v12
	s_nop 0
	v_mul_f32_e32 v12, v12, v190
	v_mul_f32_e32 v12, 0x3fb8aa3b, v12
	v_exp_f32_e32 v12, v12
	s_nop 0
	v_sub_f32_e32 v13, 1.0, v12
	v_add_f32_e32 v12, 1.0, v12
	v_mul_f32_e32 v12, v13, v12
	v_max_f32_e32 v12, 0, v12
	v_sqrt_f32_e32 v12, v12
	s_nop 0
	v_mul_f32_e32 v9, v9, v12
	v_add_f32_e32 v12, v14, v42
	v_mul_f32_e32 v12, 0xbfb8aa3b, v12
	v_exp_f32_e32 v12, v12
	v_mul_f32_e32 v9, v9, v23
	v_add_f32_e32 v12, 1.0, v12
	v_rcp_f32_e32 v12, v12
	s_nop 0
	v_mul_f32_e32 v12, v12, v191
	v_mul_f32_e32 v12, 0x3fb8aa3b, v12
	v_exp_f32_e32 v12, v12
	s_nop 0
	v_sub_f32_e32 v14, 1.0, v12
	v_add_f32_e32 v12, 1.0, v12
	v_mul_f32_e32 v12, v14, v12
	v_max_f32_e32 v12, 0, v12
	v_sqrt_f32_e32 v12, v12
	s_nop 0
	v_mul_f32_e32 v10, v10, v12
	v_add_f32_e32 v12, v15, v43
	v_mul_f32_e32 v12, 0xbfb8aa3b, v12
	v_exp_f32_e32 v12, v12
	v_mul_f32_e32 v10, v10, v24
	v_add_f32_e32 v12, 1.0, v12
	v_rcp_f32_e32 v12, v12
	s_nop 0
	v_mul_f32_e32 v12, v12, v192
	v_mul_f32_e32 v12, 0x3fb8aa3b, v12
	v_exp_f32_e32 v12, v12
	s_nop 0
	v_sub_f32_e32 v15, 1.0, v12
	v_add_f32_e32 v12, 1.0, v12
	v_mul_f32_e32 v12, v15, v12
	v_max_f32_e32 v12, 0, v12
	v_sqrt_f32_e32 v12, v12
	s_nop 0
	v_mul_f32_e32 v11, v11, v12
	v_sub_f32_e32 v12, 1.0, v4
	v_add_f32_e32 v4, 1.0, v4
	v_mul_f32_e32 v4, v12, v4
	v_max_f32_e32 v4, 0, v4
	v_sqrt_f32_e32 v4, v4
	v_mul_f32_e32 v11, v11, v19
	v_mul_f32_e32 v0, v0, v4
	v_mul_f32_e32 v19, v0, v25
	v_add_f32_e32 v0, v5, v29
	v_mul_f32_e32 v0, 0xbfb8aa3b, v0
	v_exp_f32_e32 v0, v0
	s_nop 0
	v_add_f32_e32 v0, 1.0, v0
	v_rcp_f32_e32 v0, v0
	s_nop 0
	v_mul_f32_e32 v0, v0, v189
	v_mul_f32_e32 v0, 0x3fb8aa3b, v0
	v_exp_f32_e32 v0, v0
	s_nop 0
	v_sub_f32_e32 v4, 1.0, v0
	v_add_f32_e32 v0, 1.0, v0
	v_mul_f32_e32 v0, v4, v0
	v_max_f32_e32 v0, 0, v0
	v_sqrt_f32_e32 v0, v0
	s_nop 0
	v_mul_f32_e32 v0, v1, v0
	v_mul_f32_e32 v20, v0, v20
	v_add_f32_e32 v0, v6, v30
	v_mul_f32_e32 v0, 0xbfb8aa3b, v0
	v_exp_f32_e32 v0, v0
	v_add_f32_e32 v1, v2, v34
	v_mul_f32_e32 v1, 0xbfb8aa3b, v1
	v_exp_f32_e32 v1, v1
	v_add_f32_e32 v0, 1.0, v0
	v_rcp_f32_e32 v0, v0
	v_add_f32_e32 v1, 1.0, v1
	v_rcp_f32_e32 v1, v1
	v_mul_f32_e32 v0, v0, v150
	v_mul_f32_e32 v0, 0x3fb8aa3b, v0
	v_exp_f32_e32 v0, v0
	s_nop 0
	v_sub_f32_e32 v5, 1.0, v0
	v_add_f32_e32 v0, 1.0, v0
	v_mul_f32_e32 v0, v5, v0
	v_max_f32_e32 v0, 0, v0
	v_sqrt_f32_e32 v0, v0
	s_nop 0
	v_mul_f32_e32 v0, v1, v0
	v_mul_f32_e32 v6, v0, v26
	v_add_f32_e32 v0, v7, v31
	v_mul_f32_e32 v0, 0xbfb8aa3b, v0
	v_exp_f32_e32 v0, v0
	v_add_f32_e32 v1, v3, v35
	v_mul_f32_e32 v1, 0xbfb8aa3b, v1
	v_exp_f32_e32 v1, v1
	v_add_f32_e32 v0, 1.0, v0
	v_rcp_f32_e32 v0, v0
	v_add_f32_e32 v1, 1.0, v1
	v_rcp_f32_e32 v1, v1
	v_mul_f32_e32 v0, v0, v151
	v_mul_f32_e32 v0, 0x3fb8aa3b, v0
	v_exp_f32_e32 v0, v0
	s_nop 0
	v_sub_f32_e32 v3, 1.0, v0
	v_add_f32_e32 v0, 1.0, v0
	v_mul_f32_e32 v0, v3, v0
	v_max_f32_e32 v0, 0, v0
	v_sqrt_f32_e32 v0, v0
	s_nop 0
	v_mul_f32_e32 v0, v1, v0
	v_mul_f32_e32 v7, v0, v18
	v_cvt_pk_bf16_f32 v0, v21, v13
	v_cvt_pk_bf16_f32 v1, v14, v15
	v_cvt_pk_bf16_f32 v2, v12, v4
	v_cvt_pk_bf16_f32 v3, v5, v3
	v_lshl_add_u64 v[4:5], s[20:21], 0, v[16:17]
	global_store_dwordx4 v[4:5], v[0:3], off sc0 sc1
	s_nop 1
	v_cvt_pk_bf16_f32 v0, v8, v9
	v_cvt_pk_bf16_f32 v1, v10, v11
	v_cvt_pk_bf16_f32 v2, v19, v20
	v_cvt_pk_bf16_f32 v3, v6, v7
	v_lshl_add_u64 v[4:5], s[34:35], 0, v[16:17]
	global_store_dwordx4 v[4:5], v[0:3], off sc0 sc1
	s_nop 1
	s_nop 0
	s_mov_b64 s[36:37], exec
	v_readlane_b32 s8, v254, 0
	v_readlane_b32 s9, v254, 1
	s_and_b64 s[8:9], s[36:37], s[8:9]
	s_mov_b64 exec, s[8:9]
	s_cbranch_execz .LBB0_464
	s_mov_b64 s[38:39], exec
	v_mbcnt_lo_u32_b32 v0, s38, 0
	v_mbcnt_hi_u32_b32 v0, s39, v0
	v_cmp_eq_u32_e32 vcc, 0, v0
	s_and_b64 s[8:9], exec, vcc
	s_mov_b64 exec, s[8:9]
	s_cbranch_execz .LBB0_464
	s_lshl_b32 s0, s0, 6
	s_ashr_i32 s1, s0, 31
	s_lshl_b64 s[0:1], s[0:1], 2
	v_readlane_b32 s4, v254, 51
	v_readlane_b32 s5, v254, 52
	s_add_u32 s0, s4, s0
	s_addc_u32 s1, s5, s1
	s_bcnt1_i32_b64 s8, s[38:39]
	v_mov_b32_e32 v0, s8
	s_sub_u32 s98, s0, 1
	s_subb_u32 s99, s1, 0
